# sample-row projection moved before the P1a GEMM (tail-first); mixer-B loads hoisted w/o temp reg
# speedup vs baseline: 1.0036x; 1.0036x over previous
.LBB0_168:
	s_add_u32 s62, s68, 0x1440000
	s_addc_u32 s63, s69, 0
	s_waitcnt lgkmcnt(0)
	s_add_u32 s50, s68, 0x3600000
	s_addc_u32 s51, s69, 0
	s_add_u32 s98, s68, 0x5600000
	s_addc_u32 s99, s69, 0
	s_cmp_lt_i32 s70, 2
	s_cselect_b64 s[0:1], -1, 0
	s_cmp_gt_i32 s71, 1
	s_cselect_b64 s[4:5], -1, 0
	s_and_b64 s[0:1], s[0:1], s[4:5]
	v_and_b32_e32 v233, 15, v201
	s_andn2_b64 vcc, exec, s[0:1]
	v_lshrrev_b32_e32 v232, 4, v200
	s_cbranch_vccnz .LBB0_278
	s_branch .LBB0_194
.Lp1a_gemm:
	s_cmpk_gt_i32 s2, 0x2ff
	v_readfirstlane_b32 s7, v201
	s_cbranch_scc1 .Lp1a_after
	s_waitcnt vmcnt(4)
	v_lshlrev_b32_e32 v12, 4, v201
	v_lshrrev_b32_e32 v0, 5, v201
	v_lshrrev_b32_e32 v2, 1, v201
	v_and_b32_e32 v0, 4, v0
	v_bfe_u32 v1, v201, 2, 2
	v_and_b32_e32 v2, 24, v2
	v_add_u32_e32 v8, 0x2000, v12
	v_or3_b32 v0, v0, v1, v2
	v_lshrrev_b32_e32 v1, 7, v8
	s_movk_i32 s0, 0xe0
	v_and_b32_e32 v3, 32, v201
	v_and_or_b32 v2, v1, s0, v0
	v_bitop3_b32 v9, v12, v3, 48 bitop3:0x6c
	v_and_b32_e32 v10, 64, v201
	v_bfe_u32 v11, v201, 2, 4
	s_movk_i32 s0, 0xf0
	v_or_b32_e32 v3, v9, v10
	v_and_or_b32 v1, v1, s0, v11
	v_lshl_or_b32 v130, v1, 11, v3
	v_lshrrev_b32_e32 v1, 3, v201
	s_movk_i32 s0, 0x60
	v_and_or_b32 v0, v1, s0, v0
	s_movk_i32 s0, 0x70
	s_ashr_i32 s33, s2, 31
	v_lshl_or_b32 v132, v0, 11, v3
	v_and_or_b32 v0, v1, s0, v11
	s_lshr_b32 s0, s33, 29
	s_add_i32 s0, s2, s0
	s_lshr_b32 s9, s7, 6
	s_ashr_i32 s1, s0, 3
	s_and_b32 s0, s0, -8
	s_lshr_b32 s8, s7, 8
	s_lshl_b32 s3, s9, 10
	s_sub_i32 s0, s2, s0
	s_cmp_lt_i32 s0, 0
	s_movk_i32 s4, 0x61
	s_cselect_b32 s4, s4, 0x60
	s_mul_i32 s0, s0, s4
	s_add_i32 s0, s0, s1
	v_writelane_b32 v254, s98, 0
	s_mul_hi_i32 s1, s0, 0x2aaaaaab
	s_lshr_b32 s4, s1, 31
	v_writelane_b32 v254, s99, 1
	s_ashr_i32 s1, s1, 4
	v_writelane_b32 v254, s92, 2
	s_add_i32 s1, s1, s4
	s_lshl_b32 s4, s1, 3
	v_writelane_b32 v254, s93, 3
	s_mulk_i32 s1, 0x60
	v_writelane_b32 v254, s90, 4
	s_sub_i32 s5, s0, s1
	v_writelane_b32 v254, s88, 5
	s_bfe_i32 s0, s5, 0x80000
	s_bfe_u32 s0, s0, 0x3000c
	v_writelane_b32 v254, s89, 6
	v_writelane_b32 v254, s79, 7
	s_add_i32 s0, s5, s0
	v_writelane_b32 v254, s82, 8
	s_bfe_i32 s1, s0, 0x80000
	s_and_b32 s0, s0, 0xf8
	v_writelane_b32 v254, s83, 9
	s_sub_i32 s0, s5, s0
	v_writelane_b32 v254, s86, 10
	s_sext_i32_i8 s0, s0
	s_sext_i32_i16 s1, s1
	v_writelane_b32 v254, s87, 11
	s_add_i32 s86, s4, s0
	s_ashr_i32 s87, s86, 31
	s_lshr_b32 s6, s1, 3
	s_lshl_b64 s[0:1], s[86:87], 19
	s_add_u32 s10, s80, s0
	s_addc_u32 s11, s81, s1
	s_bfe_i64 s[0:1], s[6:7], 0x100000
	s_lshl_b64 s[0:1], s[0:1], 19
	s_add_u32 s0, s84, s0
	s_addc_u32 s1, s85, s1
	s_add_i32 s43, s3, 0
	v_writelane_b32 v254, s78, 12
	s_add_i32 m0, s43, 0x10000
	s_add_i32 s12, s43, 0x12000
	v_writelane_b32 v254, s75, 13
	s_cmp_lt_i32 s5, 32
	v_writelane_b32 v254, s76, 14
	s_cselect_b32 s5, s11, s1
	s_cselect_b32 s4, s10, s0
	v_writelane_b32 v254, s77, 15
	v_lshl_or_b32 v128, v2, 11, v3
	global_load_lds_dwordx4 v132, s[4:5]
	s_mov_b32 m0, s12
	s_cselect_b32 s0, s0, s10
	s_cselect_b32 s1, s1, s11
	s_add_u32 s10, s4, 0x40000
	v_writelane_b32 v254, s74, 16
	global_load_lds_dwordx4 v128, s[4:5]
	s_addc_u32 s11, s5, 0
	s_add_i32 m0, s43, 0x14000
	v_writelane_b32 v254, s75, 17
	global_load_lds_dwordx4 v132, s[10:11]
	s_add_i32 m0, s43, 0x16000
	s_add_i32 s75, s43, 0x2000
	v_lshl_or_b32 v134, v0, 11, v3
	global_load_lds_dwordx4 v128, s[10:11]
	s_mov_b32 m0, s43
	s_add_u32 s10, s0, 0x40000
	global_load_lds_dwordx4 v134, s[0:1]
	s_mov_b32 m0, s75
	s_addc_u32 s11, s1, 0
	s_add_i32 s77, s43, 0x4000
	global_load_lds_dwordx4 v130, s[0:1]
	s_mov_b32 m0, s77
	s_add_i32 s87, s43, 0x6000
	global_load_lds_dwordx4 v134, s[10:11]
	s_mov_b32 m0, s87
	v_mov_b32_e32 v137, 0
	global_load_lds_dwordx4 v130, s[10:11]
	v_mov_b32_e32 v133, v137
	v_mov_b32_e32 v129, v137
	v_mov_b32_e32 v135, v137
	v_mov_b32_e32 v131, v137
	s_cmp_eq_u32 s8, 1
	s_movk_i32 s15, 0x61
	s_mov_b32 s95, 0
	v_lshl_add_u64 v[6:7], s[4:5], 0, v[132:133]
	v_lshl_add_u64 v[4:5], s[4:5], 0, v[128:129]
	v_lshl_add_u64 v[0:1], s[0:1], 0, v[134:135]
	s_cselect_b64 s[88:89], -1, 0
	s_cmp_lg_u32 s8, 1
	v_lshl_add_u64 v[2:3], s[0:1], 0, v[130:131]
	s_cbranch_scc1 .LBB0_172
	s_barrier

.LBB0_193:
	s_waitcnt vmcnt(0)
	v_readlane_b32 s74, v254, 16
	v_readlane_b32 s75, v254, 17
	v_readlane_b32 s76, v254, 14
	v_readlane_b32 s86, v254, 10
	v_readlane_b32 s82, v254, 8
	v_readlane_b32 s88, v254, 5
	v_readlane_b32 s92, v254, 2
	v_readlane_b32 s98, v254, 0
	v_readlane_b32 s77, v254, 15
	v_readlane_b32 s75, v254, 13
	v_readlane_b32 s78, v254, 12
	v_readlane_b32 s87, v254, 11
	v_readlane_b32 s83, v254, 9
	v_readlane_b32 s79, v254, 7
	v_readlane_b32 s89, v254, 6
	v_readlane_b32 s90, v254, 4
	v_readlane_b32 s93, v254, 3
	v_readlane_b32 s99, v254, 1
	s_barrier
	s_branch .Lp1a_after

.LBB0_224:
	s_waitcnt lgkmcnt(0)
	s_barrier
	s_branch .Lp1a_gemm

.LBB0_314:
	s_or_b64 exec, exec, s[40:41]
	v_or_b32_e32 v187, s11, v233
	v_lshlrev_b32_e32 v187, 11, v187
	v_lshl_add_u32 v187, v210, 1, v187
	v_mov_b32_e32 v250, 0
	v_mov_b32_e32 v251, 0
	v_mov_b32_e32 v252, 0
	v_mov_b32_e32 v253, 0
	s_mov_b64 s[40:41], exec
	s_and_b64 exec, exec, s[8:9]
	v_add_u32_e32 v187, 0x38000, v187
	s_nop 0
	global_load_dwordx4 v[250:253], v187, s[50:51]
	v_add_u32_e32 v187, 0xfffc8000, v187
	s_mov_b64 exec, s[40:41]
	global_load_dwordx4 v[188:191], v187, s[50:51]
	v_add_u32_e32 v187, 0x8000, v187
	global_load_dwordx4 v[192:195], v187, s[50:51]
	v_add_u32_e32 v187, 0x8000, v187
	global_load_dwordx4 v[196:199], v187, s[50:51]
	v_add_u32_e32 v187, 0x8000, v187
	global_load_dwordx4 v[228:231], v187, s[50:51]
	v_add_u32_e32 v187, 0x28000, v187
	global_load_dwordx4 v[246:249], v187, s[50:51]
	v_mul_f32_e32 v144, 0xbfb8aa3b, v128
	v_mul_f32_e32 v145, 0xbfb8aa3b, v129
	v_exp_f32_e32 v144, v144
	v_exp_f32_e32 v145, v145
	v_mul_f32_e32 v146, 0xbfb8aa3b, v130
	v_mul_f32_e32 v147, 0xbfb8aa3b, v131
	v_exp_f32_e32 v146, v146
	v_exp_f32_e32 v147, v147
	v_add_f32_e32 v144, 1.0, v144
	v_add_f32_e32 v145, 1.0, v145
	v_rcp_f32_e32 v144, v144
	v_rcp_f32_e32 v145, v145
	v_add_f32_e32 v146, 1.0, v146
	v_add_f32_e32 v147, 1.0, v147
	v_rcp_f32_e32 v146, v146
	v_rcp_f32_e32 v147, v147
	v_pk_mul_f32 v[164:165], v[128:129], v[144:145]
	v_mul_f32_e32 v144, 0xbfb8aa3b, v120
	v_mul_f32_e32 v145, 0xbfb8aa3b, v121
	v_exp_f32_e32 v144, v144
	v_exp_f32_e32 v145, v145
	v_pk_mul_f32 v[166:167], v[130:131], v[146:147]
	v_mul_f32_e32 v146, 0xbfb8aa3b, v122
	v_mul_f32_e32 v147, 0xbfb8aa3b, v123
	v_exp_f32_e32 v146, v146
	v_exp_f32_e32 v147, v147
	v_add_f32_e32 v144, 1.0, v144
	v_add_f32_e32 v145, 1.0, v145
	v_rcp_f32_e32 v144, v144
	v_rcp_f32_e32 v145, v145
	v_or_b32_e32 v162, s11, v233
	v_add_f32_e32 v146, 1.0, v146
	v_add_f32_e32 v147, 1.0, v147
	v_rcp_f32_e32 v146, v146
	v_rcp_f32_e32 v147, v147
	v_ashrrev_i32_e32 v163, 31, v162
	v_pk_mul_f32 v[170:171], v[120:121], v[144:145]
	v_lshlrev_b64 v[144:145], 11, v[162:163]
	v_lshl_add_u64 v[144:145], s[50:51], 0, v[144:145]
	v_lshlrev_b64 v[160:161], 1, v[210:211]
	v_lshl_add_u64 v[144:145], v[144:145], 0, v[160:161]
	v_pk_mul_f32 v[168:169], v[122:123], v[146:147]
	s_waitcnt vmcnt(4)
	v_mov_b32_e32 v144, v188
	v_mov_b32_e32 v145, v189
	v_mov_b32_e32 v146, v190
	v_mov_b32_e32 v147, v191
	v_add_u32_e32 v187, 0x8000, v187
	global_load_dwordx4 v[188:191], v187, s[50:51]
	v_mov_b32_e32 v173, v211
	v_mov_b32_e32 v174, v211
	v_mov_b32_e32 v175, v211
	v_mov_b32_e32 v176, v211
	v_mov_b32_e32 v177, v211
	v_mov_b32_e32 v178, v211
	v_mov_b32_e32 v179, v211
	v_pk_mul_f32 v[170:171], v[124:125], v[170:171]
	v_pk_mul_f32 v[168:169], v[126:127], v[168:169]
	v_mov_b32_e32 v184, v211
	v_mov_b32_e32 v185, v211
	s_movk_i32 s16, 0x7ff
	v_cndmask_b32_e64 v172, v144, v156, s[4:5]
	v_cndmask_b32_e64 v156, v156, v144, s[0:1]
	s_nop 0
	v_mov_b32_dpp v173, v172 row_ror:1 row_mask:0xf bank_mask:0xf
	v_mov_b32_e32 v172, v211
	s_nop 1
	v_mov_b32_dpp v172, v156 row_ror:2 row_mask:0xf bank_mask:0xf
	v_cndmask_b32_e64 v156, v145, v157, s[4:5]
	v_cndmask_b32_e64 v157, v157, v145, s[0:1]
	v_lshlrev_b32_e32 v180, 16, v172
	v_mov_b32_dpp v174, v156 row_ror:1 row_mask:0xf bank_mask:0xf
	v_mov_b32_dpp v175, v157 row_ror:2 row_mask:0xf bank_mask:0xf
	v_cndmask_b32_e64 v156, v146, v158, s[4:5]
	v_cndmask_b32_e64 v157, v158, v146, s[0:1]
	v_lshlrev_b32_e32 v158, 16, v144
	v_mov_b32_dpp v176, v156 row_ror:1 row_mask:0xf bank_mask:0xf
	v_mov_b32_dpp v177, v157 row_ror:2 row_mask:0xf bank_mask:0xf
	v_cndmask_b32_e64 v156, v147, v159, s[4:5]
	v_cndmask_b32_e64 v157, v159, v147, s[0:1]
	v_lshlrev_b32_e32 v159, 16, v173
	v_mov_b32_dpp v178, v156 row_ror:1 row_mask:0xf bank_mask:0xf
	v_mov_b32_dpp v179, v157 row_ror:2 row_mask:0xf bank_mask:0xf
	v_mov_b32_e32 v156, v152
	v_mov_b32_e32 v157, v140
	v_pk_mul_f32 v[158:159], v[156:157], v[158:159]
	v_and_b32_e32 v172, 0xffff0000, v172
	v_fma_f32 v140, v136, v180, v159
	v_add_f32_e32 v180, v158, v140
	v_and_b32_e32 v159, 0xffff0000, v173
	v_and_b32_e32 v158, 0xffff0000, v144
	v_mov_b32_e32 v140, v153
	v_pk_mul_f32 v[152:153], v[140:141], v[158:159]
	v_lshlrev_b32_e32 v158, 16, v145
	v_fma_f32 v153, v137, v172, v153
	v_add_f32_e32 v172, v152, v153
	v_lshlrev_b32_e32 v159, 16, v174
	v_mov_b32_e32 v152, v154
	v_mov_b32_e32 v153, v142
	v_lshlrev_b32_e32 v173, 16, v175
	v_pk_mul_f32 v[158:159], v[152:153], v[158:159]
	v_and_b32_e32 v175, 0xffff0000, v175
	v_fma_f32 v142, v138, v173, v159
	v_add_f32_e32 v173, v158, v142
	v_and_b32_e32 v159, 0xffff0000, v174
	v_and_b32_e32 v158, 0xffff0000, v145
	v_mov_b32_e32 v142, v155
	v_pk_mul_f32 v[154:155], v[142:143], v[158:159]
	v_lshlrev_b32_e32 v158, 16, v146
	v_fma_f32 v155, v139, v175, v155
	v_add_f32_e32 v174, v154, v155
	v_lshlrev_b32_e32 v159, 16, v176
	v_mov_b32_e32 v154, v148
	v_mov_b32_e32 v155, v116
	v_lshlrev_b32_e32 v175, 16, v177
	v_pk_mul_f32 v[158:159], v[154:155], v[158:159]
	v_and_b32_e32 v177, 0xffff0000, v177
	v_fma_f32 v116, v112, v175, v159
	v_add_f32_e32 v175, v158, v116
	v_and_b32_e32 v159, 0xffff0000, v176
	v_and_b32_e32 v158, 0xffff0000, v146
	v_mov_b32_e32 v116, v149
	v_pk_mul_f32 v[148:149], v[116:117], v[158:159]
	v_mov_b32_e32 v158, v150
	v_fma_f32 v149, v113, v177, v149
	v_add_f32_e32 v176, v148, v149
	v_lshlrev_b32_e32 v148, 16, v147
	v_lshlrev_b32_e32 v149, 16, v178
	v_mov_b32_e32 v159, v118
	v_lshlrev_b32_e32 v177, 16, v179
	v_pk_mul_f32 v[148:149], v[158:159], v[148:149]
	v_and_b32_e32 v150, 0xffff0000, v179
	v_fma_f32 v118, v114, v177, v149
	v_add_f32_e32 v177, v148, v118
	v_and_b32_e32 v149, 0xffff0000, v178
	v_and_b32_e32 v148, 0xffff0000, v147
	v_mov_b32_e32 v118, v151
	v_pk_mul_f32 v[148:149], v[118:119], v[148:149]
	v_mov_b32_e32 v179, v211
	v_fma_f32 v149, v115, v150, v149
	v_add_f32_e32 v178, v148, v149
	v_pk_mul_f32 v[148:149], v[132:133], v[164:165]
	v_pk_mul_f32 v[150:151], v[134:135], v[166:167]
	v_mul_f32_e32 v148, v148, v180
	v_mul_f32_e32 v149, v149, v172
	v_cvt_pk_bf16_f32 v148, v148, v149
	v_mul_f32_e32 v149, v150, v173
	v_mul_f32_e32 v150, v151, v174
	v_cvt_pk_bf16_f32 v149, v149, v150
	v_mul_f32_e32 v150, v170, v175
	v_mul_f32_e32 v151, v171, v176
	v_cvt_pk_bf16_f32 v150, v150, v151
	v_mul_f32_e32 v151, v168, v177
	v_mul_f32_e32 v164, v169, v178
	v_cvt_pk_bf16_f32 v151, v151, v164
	v_lshlrev_b64 v[164:165], 12, v[162:163]
	v_lshl_add_u64 v[164:165], s[12:13], 0, v[164:165]
	v_lshl_add_u64 v[164:165], v[164:165], 0, v[160:161]
	global_store_dwordx4 v[164:165], v[148:151], off offset:2048
	v_or_b32_e32 v172, 16, v162
	v_ashrrev_i32_e32 v173, 31, v172
	v_mul_f32_e32 v148, 0xbfb8aa3b, v104
	v_mul_f32_e32 v149, 0xbfb8aa3b, v105
	v_exp_f32_e32 v148, v148
	v_exp_f32_e32 v149, v149
	v_mul_f32_e32 v150, 0xbfb8aa3b, v106
	v_mul_f32_e32 v151, 0xbfb8aa3b, v107
	v_exp_f32_e32 v150, v150
	v_exp_f32_e32 v151, v151
	v_add_f32_e32 v148, 1.0, v148
	v_add_f32_e32 v149, 1.0, v149
	v_rcp_f32_e32 v148, v148
	v_rcp_f32_e32 v149, v149
	v_add_f32_e32 v150, 1.0, v150
	v_add_f32_e32 v151, 1.0, v151
	v_rcp_f32_e32 v150, v150
	v_rcp_f32_e32 v151, v151
	v_pk_mul_f32 v[164:165], v[104:105], v[148:149]
	v_mul_f32_e32 v148, 0xbfb8aa3b, v96
	v_mul_f32_e32 v149, 0xbfb8aa3b, v97
	v_exp_f32_e32 v148, v148
	v_exp_f32_e32 v149, v149
	v_pk_mul_f32 v[166:167], v[106:107], v[150:151]
	v_mul_f32_e32 v150, 0xbfb8aa3b, v98
	v_mul_f32_e32 v151, 0xbfb8aa3b, v99
	v_exp_f32_e32 v150, v150
	v_exp_f32_e32 v151, v151
	v_add_f32_e32 v148, 1.0, v148
	v_add_f32_e32 v149, 1.0, v149
	v_rcp_f32_e32 v148, v148
	v_rcp_f32_e32 v149, v149
	v_add_f32_e32 v150, 1.0, v150
	v_add_f32_e32 v151, 1.0, v151
	v_rcp_f32_e32 v150, v150
	v_rcp_f32_e32 v151, v151
	v_pk_mul_f32 v[168:169], v[96:97], v[148:149]
	v_lshlrev_b64 v[148:149], 11, v[172:173]
	v_lshl_add_u64 v[148:149], s[50:51], 0, v[148:149]
	v_lshl_add_u64 v[148:149], v[148:149], 0, v[160:161]
	v_pk_mul_f32 v[170:171], v[98:99], v[150:151]
	s_waitcnt vmcnt(5)
	v_mov_b32_e32 v148, v192
	v_mov_b32_e32 v149, v193
	v_mov_b32_e32 v150, v194
	v_mov_b32_e32 v151, v195
	v_add_u32_e32 v187, 0x8000, v187
	global_load_dwordx4 v[192:195], v187, s[50:51]
	v_mov_b32_e32 v174, v211
	v_mov_b32_e32 v175, v211
	v_mov_b32_e32 v176, v211
	v_mov_b32_e32 v177, v211
	v_mov_b32_e32 v178, v211
	v_mov_b32_e32 v180, v211
	v_pk_mul_f32 v[166:167], v[110:111], v[166:167]
	v_pk_mul_f32 v[170:171], v[102:103], v[170:171]
	v_cndmask_b32_e64 v163, v148, v144, s[4:5]
	v_cndmask_b32_e64 v144, v144, v148, s[0:1]
	s_nop 0
	v_mov_b32_dpp v174, v163 row_ror:1 row_mask:0xf bank_mask:0xf
	v_mov_b32_e32 v163, v211
	s_nop 1
	v_mov_b32_dpp v163, v144 row_ror:2 row_mask:0xf bank_mask:0xf
	v_cndmask_b32_e64 v144, v149, v145, s[4:5]
	v_cndmask_b32_e64 v145, v145, v149, s[0:1]
	s_nop 0
	v_mov_b32_dpp v175, v144 row_ror:1 row_mask:0xf bank_mask:0xf
	v_mov_b32_dpp v176, v145 row_ror:2 row_mask:0xf bank_mask:0xf
	v_cndmask_b32_e64 v144, v150, v146, s[4:5]
	v_cndmask_b32_e64 v145, v146, v150, s[0:1]
	s_nop 0
	v_mov_b32_dpp v177, v144 row_ror:1 row_mask:0xf bank_mask:0xf
	v_mov_b32_dpp v178, v145 row_ror:2 row_mask:0xf bank_mask:0xf
	v_cndmask_b32_e64 v144, v151, v147, s[4:5]
	v_cndmask_b32_e64 v145, v147, v151, s[0:1]
	v_pk_mul_f32 v[146:147], v[100:101], v[168:169]
	v_mov_b32_dpp v179, v144 row_ror:1 row_mask:0xf bank_mask:0xf
	v_mov_b32_dpp v180, v145 row_ror:2 row_mask:0xf bank_mask:0xf
	v_lshlrev_b32_e32 v145, 16, v174
	v_lshlrev_b32_e32 v144, 16, v148
	v_lshlrev_b32_e32 v168, 16, v163
	v_pk_mul_f32 v[144:145], v[156:157], v[144:145]
	v_and_b32_e32 v163, 0xffff0000, v163
	v_fma_f32 v145, v136, v168, v145
	v_add_f32_e32 v168, v144, v145
	v_and_b32_e32 v145, 0xffff0000, v174
	v_and_b32_e32 v144, 0xffff0000, v148
	v_pk_mul_f32 v[144:145], v[140:141], v[144:145]
	v_lshlrev_b32_e32 v169, 16, v176
	v_fma_f32 v145, v137, v163, v145
	v_add_f32_e32 v163, v144, v145
	v_lshlrev_b32_e32 v145, 16, v175
	v_lshlrev_b32_e32 v144, 16, v149
	v_pk_mul_f32 v[144:145], v[152:153], v[144:145]
	v_and_b32_e32 v174, 0xffff0000, v176
	v_fma_f32 v145, v138, v169, v145
	v_add_f32_e32 v169, v144, v145
	v_and_b32_e32 v145, 0xffff0000, v175
	v_and_b32_e32 v144, 0xffff0000, v149
	v_pk_mul_f32 v[144:145], v[142:143], v[144:145]
	v_lshlrev_b32_e32 v175, 16, v178
	v_fma_f32 v145, v139, v174, v145
	v_add_f32_e32 v174, v144, v145
	v_lshlrev_b32_e32 v145, 16, v177
	v_lshlrev_b32_e32 v144, 16, v150
	v_pk_mul_f32 v[144:145], v[154:155], v[144:145]
	v_and_b32_e32 v176, 0xffff0000, v178
	v_fma_f32 v145, v112, v175, v145
	v_add_f32_e32 v175, v144, v145
	v_and_b32_e32 v145, 0xffff0000, v177
	v_and_b32_e32 v144, 0xffff0000, v150
	v_pk_mul_f32 v[144:145], v[116:117], v[144:145]
	v_lshlrev_b32_e32 v177, 16, v180
	v_fma_f32 v145, v113, v176, v145
	v_add_f32_e32 v176, v144, v145
	v_lshlrev_b32_e32 v145, 16, v179
	v_lshlrev_b32_e32 v144, 16, v151
	v_pk_mul_f32 v[144:145], v[158:159], v[144:145]
	v_and_b32_e32 v178, 0xffff0000, v180
	v_fma_f32 v145, v114, v177, v145
	v_add_f32_e32 v177, v144, v145
	v_and_b32_e32 v145, 0xffff0000, v179
	v_and_b32_e32 v144, 0xffff0000, v151
	v_pk_mul_f32 v[144:145], v[118:119], v[144:145]
	v_mul_f32_e32 v146, v146, v175
	v_fma_f32 v145, v115, v178, v145
	v_add_f32_e32 v178, v144, v145
	v_pk_mul_f32 v[144:145], v[108:109], v[164:165]
	v_lshlrev_b64 v[164:165], 12, v[172:173]
	v_mul_f32_e32 v144, v144, v168
	v_mul_f32_e32 v145, v145, v163
	v_cvt_pk_bf16_f32 v144, v144, v145
	v_mul_f32_e32 v145, v166, v169
	v_mul_f32_e32 v147, v147, v176
	v_lshl_add_u64 v[164:165], s[12:13], 0, v[164:165]
	v_mul_f32_e32 v163, v167, v174
	v_cvt_pk_bf16_f32 v145, v145, v163
	v_cvt_pk_bf16_f32 v146, v146, v147
	v_mul_f32_e32 v147, v170, v177
	v_lshl_add_u64 v[164:165], v[164:165], 0, v[160:161]
	v_mul_f32_e32 v163, v171, v178
	v_cvt_pk_bf16_f32 v147, v147, v163
	global_store_dwordx4 v[164:165], v[144:147], off offset:2048
	v_or_b32_e32 v172, 32, v162
	v_ashrrev_i32_e32 v173, 31, v172
	v_mul_f32_e32 v144, 0xbfb8aa3b, v88
	v_mul_f32_e32 v145, 0xbfb8aa3b, v89
	v_exp_f32_e32 v144, v144
	v_exp_f32_e32 v145, v145
	v_mul_f32_e32 v146, 0xbfb8aa3b, v90
	v_mul_f32_e32 v147, 0xbfb8aa3b, v91
	v_exp_f32_e32 v146, v146
	v_exp_f32_e32 v147, v147
	v_add_f32_e32 v144, 1.0, v144
	v_add_f32_e32 v145, 1.0, v145
	v_rcp_f32_e32 v144, v144
	v_rcp_f32_e32 v145, v145
	v_add_f32_e32 v146, 1.0, v146
	v_add_f32_e32 v147, 1.0, v147
	v_rcp_f32_e32 v146, v146
	v_rcp_f32_e32 v147, v147
	v_pk_mul_f32 v[164:165], v[88:89], v[144:145]
	v_mul_f32_e32 v144, 0xbfb8aa3b, v80
	v_mul_f32_e32 v145, 0xbfb8aa3b, v81
	v_exp_f32_e32 v144, v144
	v_exp_f32_e32 v145, v145
	v_pk_mul_f32 v[166:167], v[90:91], v[146:147]
	v_mul_f32_e32 v146, 0xbfb8aa3b, v82
	v_mul_f32_e32 v147, 0xbfb8aa3b, v83
	v_exp_f32_e32 v146, v146
	v_exp_f32_e32 v147, v147
	v_add_f32_e32 v144, 1.0, v144
	v_add_f32_e32 v145, 1.0, v145
	v_rcp_f32_e32 v144, v144
	v_rcp_f32_e32 v145, v145
	v_add_f32_e32 v146, 1.0, v146
	v_add_f32_e32 v147, 1.0, v147
	v_rcp_f32_e32 v146, v146
	v_rcp_f32_e32 v147, v147
	v_pk_mul_f32 v[168:169], v[80:81], v[144:145]
	v_lshlrev_b64 v[144:145], 11, v[172:173]
	v_lshl_add_u64 v[144:145], s[50:51], 0, v[144:145]
	v_lshl_add_u64 v[144:145], v[144:145], 0, v[160:161]
	v_pk_mul_f32 v[170:171], v[82:83], v[146:147]
	s_waitcnt vmcnt(6)
	v_mov_b32_e32 v144, v196
	v_mov_b32_e32 v145, v197
	v_mov_b32_e32 v146, v198
	v_mov_b32_e32 v147, v199
	v_add_u32_e32 v187, 0x8000, v187
	global_load_dwordx4 v[196:199], v187, s[50:51]
	v_mov_b32_e32 v174, v211
	v_mov_b32_e32 v175, v211
	v_mov_b32_e32 v176, v211
	v_mov_b32_e32 v177, v211
	v_mov_b32_e32 v178, v211
	v_mov_b32_e32 v179, v211
	v_mov_b32_e32 v180, v211
	v_pk_mul_f32 v[166:167], v[94:95], v[166:167]
	v_pk_mul_f32 v[170:171], v[86:87], v[170:171]
	v_cndmask_b32_e64 v163, v144, v148, s[4:5]
	v_cndmask_b32_e64 v148, v148, v144, s[0:1]
	s_nop 0
	v_mov_b32_dpp v174, v163 row_ror:1 row_mask:0xf bank_mask:0xf
	v_mov_b32_e32 v163, v211
	s_nop 1
	v_mov_b32_dpp v163, v148 row_ror:2 row_mask:0xf bank_mask:0xf
	v_cndmask_b32_e64 v148, v145, v149, s[4:5]
	v_cndmask_b32_e64 v149, v149, v145, s[0:1]
	s_nop 0
	v_mov_b32_dpp v175, v148 row_ror:1 row_mask:0xf bank_mask:0xf
	v_mov_b32_dpp v176, v149 row_ror:2 row_mask:0xf bank_mask:0xf
	v_cndmask_b32_e64 v148, v146, v150, s[4:5]
	v_cndmask_b32_e64 v149, v150, v146, s[0:1]
	s_nop 0
	v_mov_b32_dpp v177, v148 row_ror:1 row_mask:0xf bank_mask:0xf
	v_mov_b32_dpp v178, v149 row_ror:2 row_mask:0xf bank_mask:0xf
	v_cndmask_b32_e64 v148, v147, v151, s[4:5]
	v_cndmask_b32_e64 v149, v151, v147, s[0:1]
	v_pk_mul_f32 v[150:151], v[84:85], v[168:169]
	v_mov_b32_dpp v179, v148 row_ror:1 row_mask:0xf bank_mask:0xf
	v_mov_b32_dpp v180, v149 row_ror:2 row_mask:0xf bank_mask:0xf
	v_lshlrev_b32_e32 v149, 16, v174
	v_lshlrev_b32_e32 v148, 16, v144
	v_lshlrev_b32_e32 v168, 16, v163
	v_pk_mul_f32 v[148:149], v[156:157], v[148:149]
	v_and_b32_e32 v163, 0xffff0000, v163
	v_fma_f32 v149, v136, v168, v149
	v_add_f32_e32 v168, v148, v149
	v_and_b32_e32 v149, 0xffff0000, v174
	v_and_b32_e32 v148, 0xffff0000, v144
	v_pk_mul_f32 v[148:149], v[140:141], v[148:149]
	v_lshlrev_b32_e32 v169, 16, v176
	v_fma_f32 v149, v137, v163, v149
	v_add_f32_e32 v163, v148, v149
	v_lshlrev_b32_e32 v149, 16, v175
	v_lshlrev_b32_e32 v148, 16, v145
	v_pk_mul_f32 v[148:149], v[152:153], v[148:149]
	v_and_b32_e32 v174, 0xffff0000, v176
	v_fma_f32 v149, v138, v169, v149
	v_add_f32_e32 v169, v148, v149
	v_and_b32_e32 v149, 0xffff0000, v175
	v_and_b32_e32 v148, 0xffff0000, v145
	v_pk_mul_f32 v[148:149], v[142:143], v[148:149]
	v_lshlrev_b32_e32 v175, 16, v178
	v_fma_f32 v149, v139, v174, v149
	v_add_f32_e32 v174, v148, v149
	v_lshlrev_b32_e32 v149, 16, v177
	v_lshlrev_b32_e32 v148, 16, v146
	v_pk_mul_f32 v[148:149], v[154:155], v[148:149]
	v_and_b32_e32 v176, 0xffff0000, v178
	v_fma_f32 v149, v112, v175, v149
	v_add_f32_e32 v175, v148, v149
	v_and_b32_e32 v149, 0xffff0000, v177
	v_and_b32_e32 v148, 0xffff0000, v146
	v_pk_mul_f32 v[148:149], v[116:117], v[148:149]
	v_lshlrev_b32_e32 v177, 16, v180
	v_fma_f32 v149, v113, v176, v149
	v_add_f32_e32 v176, v148, v149
	v_lshlrev_b32_e32 v149, 16, v179
	v_lshlrev_b32_e32 v148, 16, v147
	v_pk_mul_f32 v[148:149], v[158:159], v[148:149]
	v_and_b32_e32 v178, 0xffff0000, v180
	v_fma_f32 v149, v114, v177, v149
	v_add_f32_e32 v177, v148, v149
	v_and_b32_e32 v149, 0xffff0000, v179
	v_and_b32_e32 v148, 0xffff0000, v147
	v_pk_mul_f32 v[148:149], v[118:119], v[148:149]
	v_mul_f32_e32 v150, v150, v175
	v_fma_f32 v149, v115, v178, v149
	v_add_f32_e32 v178, v148, v149
	v_pk_mul_f32 v[148:149], v[92:93], v[164:165]
	v_mul_f32_e32 v151, v151, v176
	v_mul_f32_e32 v148, v148, v168
	v_mul_f32_e32 v149, v149, v163
	v_or_b32_e32 v168, 48, v162
	v_cvt_pk_bf16_f32 v148, v148, v149
	v_mul_f32_e32 v149, v166, v169
	v_mul_f32_e32 v163, v167, v174
	v_lshlrev_b64 v[164:165], 12, v[172:173]
	v_ashrrev_i32_e32 v169, 31, v168
	v_cvt_pk_bf16_f32 v149, v149, v163
	v_cvt_pk_bf16_f32 v150, v150, v151
	v_mul_f32_e32 v151, v170, v177
	v_mul_f32_e32 v163, v171, v178
	v_lshl_add_u64 v[164:165], s[12:13], 0, v[164:165]
	v_lshlrev_b64 v[170:171], 11, v[168:169]
	v_lshl_add_u64 v[164:165], v[164:165], 0, v[160:161]
	v_lshl_add_u64 v[170:171], s[50:51], 0, v[170:171]
	v_cvt_pk_bf16_f32 v151, v151, v163
	global_store_dwordx4 v[164:165], v[148:151], off offset:2048
	v_lshl_add_u64 v[170:171], v[170:171], 0, v[160:161]
	s_waitcnt vmcnt(7)
	v_mov_b32_e32 v176, v228
	v_mov_b32_e32 v177, v229
	v_mov_b32_e32 v178, v230
	v_mov_b32_e32 v179, v231
	v_mul_f32_e32 v148, 0xbfb8aa3b, v72
	v_mul_f32_e32 v149, 0xbfb8aa3b, v73
	v_exp_f32_e32 v148, v148
	v_exp_f32_e32 v149, v149
	v_mul_f32_e32 v150, 0xbfb8aa3b, v74
	v_mul_f32_e32 v151, 0xbfb8aa3b, v75
	v_add_f32_e32 v148, 1.0, v148
	v_add_f32_e32 v149, 1.0, v149
	v_rcp_f32_e32 v148, v148
	v_rcp_f32_e32 v149, v149
	v_exp_f32_e32 v150, v150
	v_exp_f32_e32 v151, v151
	v_mov_b32_e32 v170, v211
	v_pk_mul_f32 v[164:165], v[72:73], v[148:149]
	v_mul_f32_e32 v148, 0xbfb8aa3b, v64
	v_mul_f32_e32 v149, 0xbfb8aa3b, v65
	v_exp_f32_e32 v148, v148
	v_exp_f32_e32 v149, v149
	v_add_f32_e32 v150, 1.0, v150
	v_add_f32_e32 v151, 1.0, v151
	v_add_f32_e32 v148, 1.0, v148
	v_add_f32_e32 v149, 1.0, v149
	v_rcp_f32_e32 v148, v148
	v_rcp_f32_e32 v149, v149
	v_rcp_f32_e32 v150, v150
	v_rcp_f32_e32 v151, v151
	v_mov_b32_e32 v172, v211
	v_mov_b32_e32 v173, v211
	v_mov_b32_e32 v174, v211
	v_mov_b32_e32 v175, v211
	v_pk_mul_f32 v[148:149], v[64:65], v[148:149]
	v_pk_mul_f32 v[166:167], v[74:75], v[150:151]
	v_mul_f32_e32 v150, 0xbfb8aa3b, v66
	v_mul_f32_e32 v151, 0xbfb8aa3b, v67
	v_pk_mul_f32 v[182:183], v[68:69], v[148:149]
	v_exp_f32_e32 v150, v150
	v_exp_f32_e32 v151, v151
	v_pk_mul_f32 v[164:165], v[76:77], v[164:165]
	v_pk_mul_f32 v[166:167], v[78:79], v[166:167]
	v_add_f32_e32 v150, 1.0, v150
	v_add_f32_e32 v151, 1.0, v151
	v_rcp_f32_e32 v150, v150
	v_rcp_f32_e32 v151, v151
	v_cndmask_b32_e64 v163, v176, v144, s[4:5]
	v_cndmask_b32_e64 v144, v144, v176, s[0:1]
	s_nop 0
	v_mov_b32_dpp v170, v163 row_ror:1 row_mask:0xf bank_mask:0xf
	v_mov_b32_e32 v163, v211
	v_and_b32_e32 v171, 0xffff0000, v170
	v_pk_mul_f32 v[150:151], v[66:67], v[150:151]
	v_mov_b32_dpp v163, v144 row_ror:2 row_mask:0xf bank_mask:0xf
	v_cndmask_b32_e64 v144, v177, v145, s[4:5]
	v_cndmask_b32_e64 v145, v145, v177, s[0:1]
	v_lshlrev_b32_e32 v148, 16, v163
	v_mov_b32_dpp v172, v144 row_ror:1 row_mask:0xf bank_mask:0xf
	v_mov_b32_dpp v173, v145 row_ror:2 row_mask:0xf bank_mask:0xf
	v_cndmask_b32_e64 v144, v178, v146, s[4:5]
	v_cndmask_b32_e64 v145, v146, v178, s[0:1]
	v_pk_mul_f32 v[180:181], v[70:71], v[150:151]
	v_mov_b32_dpp v174, v144 row_ror:1 row_mask:0xf bank_mask:0xf
	v_mov_b32_dpp v175, v145 row_ror:2 row_mask:0xf bank_mask:0xf
	v_cndmask_b32_e64 v144, v179, v147, s[4:5]
	v_cndmask_b32_e64 v145, v147, v179, s[0:1]
	s_nop 0
	v_mov_b32_dpp v184, v144 row_ror:1 row_mask:0xf bank_mask:0xf
	v_mov_b32_dpp v185, v145 row_ror:2 row_mask:0xf bank_mask:0xf
	v_lshlrev_b32_e32 v145, 16, v170
	v_lshlrev_b32_e32 v144, 16, v176
	v_pk_mul_f32 v[146:147], v[156:157], v[144:145]
	v_and_b32_e32 v170, 0xffff0000, v176
	v_fma_f32 v145, v136, v148, v147
	v_add_f32_e32 v186, v146, v145
	v_and_b32_e32 v145, 0xffff0000, v163
	v_pk_mul_f32 v[146:147], v[140:141], v[170:171]
	s_nop 0
	v_fma_f32 v145, v137, v145, v147
	v_add_f32_e32 v163, v146, v145
	v_lshlrev_b32_e32 v147, 16, v172
	v_lshlrev_b32_e32 v146, 16, v177
	v_lshlrev_b32_e32 v145, 16, v173
	v_pk_mul_f32 v[148:149], v[152:153], v[146:147]
	v_mul_f32_e32 v163, v165, v163
	v_fma_f32 v145, v138, v145, v149
	v_add_f32_e32 v147, v148, v145
	v_and_b32_e32 v145, 0xffff0000, v173
	v_and_b32_e32 v173, 0xffff0000, v172
	v_and_b32_e32 v172, 0xffff0000, v177
	v_pk_mul_f32 v[148:149], v[142:143], v[172:173]
	v_mul_f32_e32 v147, v166, v147
	v_fma_f32 v145, v139, v145, v149
	v_add_f32_e32 v171, v148, v145
	v_lshlrev_b32_e32 v149, 16, v174
	v_lshlrev_b32_e32 v148, 16, v178
	v_lshlrev_b32_e32 v145, 16, v175
	v_pk_mul_f32 v[150:151], v[154:155], v[148:149]
	s_nop 0
	v_fma_f32 v145, v112, v145, v151
	v_add_f32_e32 v149, v150, v145
	v_and_b32_e32 v145, 0xffff0000, v175
	v_and_b32_e32 v175, 0xffff0000, v174
	v_and_b32_e32 v174, 0xffff0000, v178
	v_pk_mul_f32 v[150:151], v[116:117], v[174:175]
	s_nop 0
	v_fma_f32 v145, v113, v145, v151
	v_add_f32_e32 v173, v150, v145
	v_lshlrev_b32_e32 v151, 16, v184
	v_lshlrev_b32_e32 v150, 16, v179
	v_lshlrev_b32_e32 v145, 16, v185
	v_pk_mul_f32 v[176:177], v[158:159], v[150:151]
	s_nop 0
	v_fma_f32 v145, v114, v145, v177
	v_add_f32_e32 v151, v176, v145
	v_and_b32_e32 v177, 0xffff0000, v184
	v_and_b32_e32 v176, 0xffff0000, v179
	v_and_b32_e32 v145, 0xffff0000, v185
	v_pk_mul_f32 v[178:179], v[118:119], v[176:177]
	s_nop 0
	v_fma_f32 v145, v115, v145, v179
	v_add_f32_e32 v175, v178, v145
	v_bitop3_b32 v145, v162, s16, 48 bitop3:0xc8
	v_mul_f32_e32 v162, v164, v186
	v_cvt_pk_bf16_f32 v162, v162, v163
	v_mul_f32_e32 v163, v167, v171
	v_lshlrev_b64 v[166:167], 12, v[168:169]
	v_lshl_add_u64 v[166:167], s[12:13], 0, v[166:167]
	s_movk_i32 s16, 0x7fd
	v_cvt_pk_bf16_f32 v163, v147, v163
	v_mul_f32_e32 v147, v182, v149
	v_mul_f32_e32 v149, v183, v173
	v_lshl_add_u64 v[166:167], v[166:167], 0, v[160:161]
	v_cmp_lt_u32_e32 vcc, s16, v145
	v_cvt_pk_bf16_f32 v164, v147, v149
	v_mul_f32_e32 v147, v180, v151
	v_mul_f32_e32 v149, v181, v175
	v_cvt_pk_bf16_f32 v165, v147, v149
	global_store_dwordx4 v[166:167], v[162:165], off offset:2048
	s_and_saveexec_b64 s[40:41], vcc
	s_cbranch_execz .LBB0_316
	v_lshrrev_b32_e32 v147, 21, v169
	v_add_u32_e32 v147, v168, v147
	v_ashrrev_i32_e32 v162, 11, v147
	v_ashrrev_i32_e32 v163, 31, v162
	v_add_u32_e32 v164, 0xfffff802, v145
	v_mov_b32_e32 v165, v211
	v_lshlrev_b64 v[162:163], 13, v[162:163]
	v_lshl_add_u64 v[162:163], s[18:19], 0, v[162:163]
	v_lshlrev_b64 v[164:165], 12, v[164:165]
	v_lshl_add_u64 v[162:163], v[162:163], 0, v[164:165]
	v_lshl_add_u64 v[162:163], v[210:211], 2, v[162:163]
	v_mov_b32_e32 v145, v170
	v_mov_b32_e32 v147, v172
	v_mov_b32_e32 v149, v174
	v_mov_b32_e32 v151, v176
	global_store_dwordx4 v[162:163], v[144:147], off
	global_store_dwordx4 v[162:163], v[148:151], off offset:16
